# attention: softmax cross-half max/sum via permlane32 swap; V^T staging key pairs merged (DPP row_ror:8 + v_perm) -> ds_write_b32 instead of b16
# baseline (speedup 1.0000x reference)
.LBB0_812:
	s_or_b64 exec, exec, s[52:53]
	s_ashr_i32 s49, s48, 31
	s_lshl_b64 s[48:49], s[48:49], 2
	s_add_u32 s48, s3, s48
	s_addc_u32 s49, s82, s49
	s_waitcnt lgkmcnt(0)
	s_barrier
	global_load_dword v149, v195, s[48:49]
	ds_read_b128 v[2:5], v142
	ds_read_b128 v[6:9], v142 offset:32
	s_waitcnt lgkmcnt(1)
	v_mfma_f32_32x32x16_bf16 v[66:81], v[2:5], v[34:37], 0
	ds_read_b128 v[2:5], v142 offset:64
	v_lshl_add_u64 v[126:127], s[50:51], 1, v[118:119]
	s_and_b64 s[48:49], vcc, s[12:13]
	s_and_b64 s[50:51], vcc, s[14:15]
	s_and_b64 s[52:53], vcc, s[16:17]
	s_and_b64 s[54:55], vcc, s[18:19]
	s_and_b64 s[56:57], vcc, s[20:21]
	s_waitcnt lgkmcnt(1)
	v_mfma_f32_32x32x16_bf16 v[66:81], v[6:9], v[106:109], v[66:81]
	s_and_b64 s[58:59], vcc, s[22:23]
	s_and_b64 s[60:61], vcc, s[24:25]
	s_and_b64 s[62:63], vcc, s[26:27]
	s_and_b64 s[64:65], vcc, s[28:29]
	s_and_b64 s[66:67], vcc, s[30:31]
	s_and_b64 s[68:69], vcc, s[34:35]
	s_and_b64 s[70:71], vcc, s[36:37]
	s_waitcnt lgkmcnt(0)
	v_mfma_f32_32x32x16_bf16 v[66:81], v[2:5], v[102:105], v[66:81]
	ds_read_b128 v[2:5], v142 offset:96
	s_and_b64 s[72:73], vcc, s[38:39]
	s_and_b64 s[74:75], vcc, s[42:43]
	s_and_b64 s[76:77], vcc, s[44:45]
	s_and_b64 s[78:79], vcc, s[0:1]
	s_or_b32 s80, s80, s96
	s_cmp_eq_u32 s80, 0
	s_waitcnt lgkmcnt(0)
	v_mfma_f32_32x32x16_bf16 v[66:81], v[2:5], v[98:101], v[66:81]
	ds_read_b128 v[2:5], v143
	ds_read_b128 v[6:9], v143 offset:32
	s_cselect_b64 s[80:81], -1, 0
	s_mov_b32 s94, 0x3fb8aa3b
	v_or_b32_e32 v152, s97, v150
	s_add_i32 s2, s2, s86
	s_cmpk_lt_i32 s2, 0x200
	s_nop 4
	v_cndmask_b32_e64 v67, v245, v67, s[50:51]
	s_waitcnt lgkmcnt(1)
	v_mfma_f32_32x32x16_bf16 v[50:65], v[2:5], v[34:37], 0
	ds_read_b128 v[2:5], v143 offset:64
	v_cndmask_b32_e64 v68, v245, v68, s[52:53]
	v_cndmask_b32_e64 v69, v245, v69, s[54:55]
	v_cndmask_b32_e64 v70, v245, v70, s[56:57]
	v_cndmask_b32_e64 v71, v245, v71, s[58:59]
	v_cndmask_b32_e64 v72, v245, v72, s[60:61]
	v_cndmask_b32_e64 v75, v245, v75, s[66:67]
	s_waitcnt lgkmcnt(1)
	v_mfma_f32_32x32x16_bf16 v[50:65], v[6:9], v[106:109], v[50:65]
	v_cndmask_b32_e64 v78, v245, v78, s[72:73]
	v_cndmask_b32_e64 v79, v245, v79, s[74:75]
	v_cndmask_b32_e64 v80, v245, v80, s[76:77]
	v_cndmask_b32_e64 v81, v245, v81, s[78:79]
	s_waitcnt vmcnt(0)
	v_mul_f32_e32 v151, 0x3fb8aa3b, v149
	s_waitcnt lgkmcnt(0)
	v_mfma_f32_32x32x16_bf16 v[50:65], v[2:5], v[102:105], v[50:65]
	ds_read_b128 v[2:5], v143 offset:96
	s_waitcnt lgkmcnt(0)
	v_mfma_f32_32x32x16_bf16 v[50:65], v[2:5], v[98:101], v[50:65]
	ds_read_b128 v[2:5], v144
	ds_read_b128 v[6:9], v144 offset:32
	s_waitcnt lgkmcnt(1)
	v_mfma_f32_32x32x16_bf16 v[18:33], v[2:5], v[34:37], 0
	ds_read_b128 v[2:5], v144 offset:64
	s_nop 6
	v_cndmask_b32_e32 v50, v245, v50, vcc
	v_cndmask_b32_e32 v54, v245, v54, vcc
	v_cndmask_b32_e32 v59, v245, v59, vcc
	v_cndmask_b32_e32 v60, v245, v60, vcc
	v_cndmask_b32_e32 v153, v245, v61, vcc
	v_cndmask_b32_e32 v63, v245, v63, vcc
	s_waitcnt lgkmcnt(1)
	v_mfma_f32_32x32x16_bf16 v[18:33], v[6:9], v[106:109], v[18:33]
	v_cndmask_b32_e32 v65, v245, v65, vcc
	s_waitcnt lgkmcnt(0)
	v_mfma_f32_32x32x16_bf16 v[18:33], v[2:5], v[102:105], v[18:33]
	ds_read_b128 v[2:5], v144 offset:96
	s_waitcnt lgkmcnt(0)
	v_mfma_f32_32x32x16_bf16 v[18:33], v[2:5], v[98:101], v[18:33]
	ds_read_b128 v[2:5], v145
	ds_read_b128 v[38:41], v145 offset:32
	s_waitcnt lgkmcnt(1)
	v_mfma_f32_32x32x16_bf16 v[2:17], v[2:5], v[34:37], 0
	s_nop 7
	v_cndmask_b32_e64 v158, v20, v245, s[80:81]
	v_cndmask_b32_e64 v159, v21, v245, s[80:81]
	v_cndmask_b32_e64 v160, v22, v245, s[80:81]
	v_cndmask_b32_e64 v161, v23, v245, s[80:81]
	v_cndmask_b32_e64 v162, v24, v245, s[80:81]
	v_cndmask_b32_e64 v163, v25, v245, s[80:81]
	v_cndmask_b32_e64 v164, v26, v245, s[80:81]
	s_waitcnt lgkmcnt(0)
	v_mfma_f32_32x32x16_bf16 v[2:17], v[38:41], v[106:109], v[2:17]
	ds_read_b128 v[38:41], v145 offset:64
	v_cndmask_b32_e64 v165, v27, v245, s[80:81]
	v_cndmask_b32_e64 v166, v28, v245, s[80:81]
	v_cndmask_b32_e64 v167, v29, v245, s[80:81]
	v_cndmask_b32_e64 v168, v30, v245, s[80:81]
	s_waitcnt lgkmcnt(0)
	v_mfma_f32_32x32x16_bf16 v[2:17], v[38:41], v[102:105], v[2:17]
	ds_read_b128 v[38:41], v145 offset:96
	s_waitcnt lgkmcnt(0)
	v_mfma_f32_32x32x16_bf16 v[2:17], v[38:41], v[98:101], v[2:17]
	ds_read_b128 v[38:41], v146
	ds_read_b128 v[154:157], v146 offset:32
	s_waitcnt lgkmcnt(1)
	v_mfma_f32_32x32x16_bf16 v[34:49], v[38:41], v[34:37], 0
	s_nop 7
	v_cndmask_b32_e64 v61, v5, v245, s[80:81]
	v_cndmask_b32_e64 v30, v14, v245, s[80:81]
	v_cndmask_b32_e64 v29, v15, v245, s[80:81]
	v_cndmask_b32_e64 v28, v16, v245, s[80:81]
	v_cndmask_b32_e64 v27, v17, v245, s[80:81]
	s_waitcnt lgkmcnt(0)
	v_mfma_f32_32x32x16_bf16 v[34:49], v[154:157], v[106:109], v[34:49]
	ds_read_b128 v[106:109], v146 offset:64
	v_cndmask_b32_e32 v154, v245, v62, vcc
	v_cndmask_b32_e32 v155, v245, v64, vcc
	v_cndmask_b32_e64 v156, v18, v245, s[80:81]
	v_cndmask_b32_e64 v157, v19, v245, s[80:81]
	v_cndmask_b32_e64 v64, v4, v245, s[80:81]
	s_waitcnt lgkmcnt(0)
	v_mfma_f32_32x32x16_bf16 v[34:49], v[106:109], v[102:105], v[34:49]
	ds_read_b128 v[102:105], v146 offset:96
	v_cndmask_b32_e32 v106, v245, v55, vcc
	v_cndmask_b32_e32 v107, v245, v56, vcc
	v_cndmask_b32_e32 v108, v245, v57, vcc
	v_cndmask_b32_e32 v109, v245, v58, vcc
	v_cndmask_b32_e64 v58, v6, v245, s[80:81]
	v_cndmask_b32_e64 v57, v7, v245, s[80:81]
	s_waitcnt lgkmcnt(0)
	v_mfma_f32_32x32x16_bf16 v[34:49], v[102:105], v[98:101], v[34:49]
	v_cndmask_b32_e64 v98, v245, v66, s[48:49]
	v_max3_f32 v66, v151, v98, v67
	v_max3_f32 v66, v66, v68, v69
	v_max3_f32 v66, v66, v70, v71
	v_cndmask_b32_e64 v99, v245, v73, s[62:63]
	v_max3_f32 v66, v66, v72, v99
	v_cndmask_b32_e64 v100, v245, v74, s[64:65]
	v_max3_f32 v66, v66, v100, v75
	v_cndmask_b32_e64 v101, v245, v76, s[68:69]
	v_cndmask_b32_e64 v102, v245, v77, s[70:71]
	v_max3_f32 v66, v66, v101, v102
	v_max3_f32 v66, v66, v78, v79
	v_max3_f32 v66, v66, v80, v81
	v_cndmask_b32_e32 v103, v245, v51, vcc
	v_max3_f32 v51, v66, v50, v103
	v_cndmask_b32_e32 v104, v245, v52, vcc
	v_cndmask_b32_e32 v105, v245, v53, vcc
	v_max3_f32 v51, v51, v104, v105
	v_max3_f32 v51, v51, v54, v106
	v_max3_f32 v51, v51, v107, v108
	v_max3_f32 v51, v51, v109, v59
	v_max3_f32 v51, v51, v60, v153
	v_max3_f32 v51, v51, v154, v63
	v_max3_f32 v51, v51, v155, v65
	v_max3_f32 v18, v51, v156, v157
	v_max3_f32 v18, v18, v158, v159
	v_max3_f32 v18, v18, v160, v161
	v_max3_f32 v18, v18, v162, v163
	v_max3_f32 v18, v18, v164, v165
	v_max3_f32 v18, v18, v166, v167
	v_cndmask_b32_e64 v77, v31, v245, s[80:81]
	v_max3_f32 v18, v18, v168, v77
	v_cndmask_b32_e64 v76, v32, v245, s[80:81]
	v_cndmask_b32_e64 v74, v33, v245, s[80:81]
	v_max3_f32 v18, v18, v76, v74
	v_cndmask_b32_e64 v73, v2, v245, s[80:81]
	v_cndmask_b32_e64 v66, v3, v245, s[80:81]
	v_max3_f32 v2, v18, v73, v66
	v_max3_f32 v2, v2, v64, v61
	v_max3_f32 v2, v2, v58, v57
	v_cndmask_b32_e64 v55, v8, v245, s[80:81]
	v_cndmask_b32_e64 v53, v9, v245, s[80:81]
	v_max3_f32 v2, v2, v55, v53
	v_cndmask_b32_e64 v52, v10, v245, s[80:81]
	v_cndmask_b32_e64 v33, v11, v245, s[80:81]
	v_max3_f32 v2, v2, v52, v33
	v_cndmask_b32_e64 v32, v12, v245, s[80:81]
	v_cndmask_b32_e64 v31, v13, v245, s[80:81]
	v_max3_f32 v2, v2, v32, v31
	v_max3_f32 v2, v2, v30, v29
	v_max3_f32 v2, v2, v28, v27
	v_cndmask_b32_e64 v26, v34, v245, s[12:13]
	v_cndmask_b32_e64 v25, v245, v35, s[46:47]
	v_max3_f32 v2, v2, v26, v25
	v_cndmask_b32_e64 v24, v36, v245, s[16:17]
	v_cndmask_b32_e64 v23, v37, v245, s[18:19]
	v_max3_f32 v2, v2, v24, v23
	v_cndmask_b32_e64 v22, v38, v245, s[20:21]
	v_cndmask_b32_e64 v21, v39, v245, s[22:23]
	v_max3_f32 v2, v2, v22, v21
	v_cndmask_b32_e64 v20, v40, v245, s[24:25]
	v_cndmask_b32_e64 v19, v41, v245, s[26:27]
	v_max3_f32 v2, v2, v20, v19
	v_cndmask_b32_e64 v18, v42, v245, s[28:29]
	v_cndmask_b32_e64 v17, v43, v245, s[30:31]
	v_max3_f32 v2, v2, v18, v17
	v_cndmask_b32_e64 v16, v44, v245, s[34:35]
	v_cndmask_b32_e64 v15, v45, v245, s[36:37]
	v_max3_f32 v2, v2, v16, v15
	v_cndmask_b32_e64 v14, v46, v245, s[38:39]
	v_cndmask_b32_e64 v13, v47, v245, s[42:43]
	v_max3_f32 v2, v2, v14, v13
	v_cndmask_b32_e64 v12, v48, v245, s[44:45]
	v_cndmask_b32_e64 v11, v49, v245, s[0:1]
	v_max3_f32 v2, v2, v12, v11
	v_mov_b32_e32 v3, v2
	v_mov_b32_e32 v206, v2
	s_nop 1
	v_permlane32_swap_b32 v3, v206
	v_max_f32_e32 v10, v3, v206
	v_sub_f32_e32 v2, v98, v10
	v_exp_f32_e32 v2, v2
	v_sub_f32_e32 v3, v67, v10
	v_exp_f32_e32 v3, v3
	v_sub_f32_e32 v35, v100, v10
	v_add_f32_e32 v4, 0, v2
	v_exp_f32_e32 v35, v35
	v_add_f32_e32 v5, v3, v4
	v_sub_f32_e32 v4, v68, v10
	v_exp_f32_e32 v4, v4
	v_sub_f32_e32 v36, v75, v10
	v_exp_f32_e32 v36, v36
	v_sub_f32_e32 v37, v101, v10
	v_add_f32_e32 v6, v4, v5
	v_sub_f32_e32 v5, v69, v10
	v_exp_f32_e32 v5, v5
	v_exp_f32_e32 v38, v37
	v_sub_f32_e32 v37, v102, v10
	v_exp_f32_e32 v39, v37
	v_add_f32_e32 v7, v5, v6
	v_sub_f32_e32 v6, v70, v10
	v_exp_f32_e32 v6, v6
	v_sub_f32_e32 v37, v78, v10
	v_exp_f32_e32 v40, v37
	v_sub_f32_e32 v37, v79, v10
	v_add_f32_e32 v8, v6, v7
	v_sub_f32_e32 v7, v71, v10
	v_exp_f32_e32 v7, v7
	v_exp_f32_e32 v45, v37
	v_sub_f32_e32 v37, v80, v10
	v_exp_f32_e32 v48, v37
	v_add_f32_e32 v9, v7, v8
	v_sub_f32_e32 v8, v72, v10
	v_exp_f32_e32 v8, v8
	v_sub_f32_e32 v37, v81, v10
	v_exp_f32_e32 v51, v37
	v_sub_f32_e32 v37, v50, v10
	v_add_f32_e32 v34, v8, v9
	v_sub_f32_e32 v9, v99, v10
	v_exp_f32_e32 v9, v9
	v_exp_f32_e32 v37, v37
	v_sub_f32_e32 v41, v103, v10
	v_exp_f32_e32 v41, v41
	v_add_f32_e32 v34, v9, v34
	v_add_f32_e32 v34, v35, v34
	v_add_f32_e32 v34, v36, v34
	v_add_f32_e32 v34, v38, v34
	v_add_f32_e32 v34, v39, v34
	v_add_f32_e32 v34, v40, v34
	v_add_f32_e32 v34, v45, v34
	v_sub_f32_e32 v42, v104, v10
	v_add_f32_e32 v34, v48, v34
	v_exp_f32_e32 v43, v42
	v_sub_f32_e32 v42, v105, v10
	v_add_f32_e32 v34, v51, v34
	v_exp_f32_e32 v44, v42
	v_sub_f32_e32 v42, v54, v10
	v_add_f32_e32 v34, v37, v34
	v_exp_f32_e32 v47, v42
	v_sub_f32_e32 v42, v106, v10
	v_add_f32_e32 v34, v41, v34
	v_exp_f32_e32 v56, v42
	v_sub_f32_e32 v42, v107, v10
	v_add_f32_e32 v34, v43, v34
	v_exp_f32_e32 v62, v42
	v_sub_f32_e32 v42, v108, v10
	v_add_f32_e32 v34, v44, v34
	v_exp_f32_e32 v67, v42
	v_sub_f32_e32 v42, v109, v10
	v_add_f32_e32 v34, v47, v34
	v_exp_f32_e32 v42, v42
	v_sub_f32_e32 v46, v59, v10
	v_add_f32_e32 v34, v56, v34
	v_exp_f32_e32 v46, v46
	v_sub_f32_e32 v49, v60, v10
	v_add_f32_e32 v34, v62, v34
	v_exp_f32_e32 v50, v49
	v_sub_f32_e32 v49, v153, v10
	v_add_f32_e32 v34, v67, v34
	v_exp_f32_e32 v54, v49
	v_sub_f32_e32 v49, v154, v10
	v_add_f32_e32 v34, v42, v34
	v_exp_f32_e32 v59, v49
	v_sub_f32_e32 v49, v63, v10
	v_add_f32_e32 v34, v46, v34
	v_exp_f32_e32 v69, v49
	v_sub_f32_e32 v49, v155, v10
	v_add_f32_e32 v34, v50, v34
	v_exp_f32_e32 v72, v49
	v_sub_f32_e32 v49, v65, v10
	v_add_f32_e32 v34, v54, v34
	v_exp_f32_e32 v78, v49
	v_sub_f32_e32 v49, v156, v10
	v_add_f32_e32 v34, v59, v34
	v_exp_f32_e32 v49, v49
	v_sub_f32_e32 v60, v157, v10
	v_add_f32_e32 v34, v69, v34
	v_exp_f32_e32 v60, v60
	v_sub_f32_e32 v63, v158, v10
	v_add_f32_e32 v34, v72, v34
	v_exp_f32_e32 v65, v63
	v_sub_f32_e32 v63, v159, v10
	v_add_f32_e32 v34, v78, v34
	v_exp_f32_e32 v68, v63
	v_sub_f32_e32 v63, v160, v10
	v_add_f32_e32 v34, v49, v34
	v_exp_f32_e32 v71, v63
	v_sub_f32_e32 v63, v161, v10
	v_add_f32_e32 v34, v60, v34
	v_exp_f32_e32 v98, v63
	v_sub_f32_e32 v63, v162, v10
	v_add_f32_e32 v34, v65, v34
	v_exp_f32_e32 v103, v63
	v_sub_f32_e32 v63, v163, v10
	v_add_f32_e32 v34, v68, v34
	v_exp_f32_e32 v104, v63
	v_sub_f32_e32 v63, v164, v10
	v_add_f32_e32 v34, v71, v34
	v_exp_f32_e32 v63, v63
	v_sub_f32_e32 v70, v165, v10
	v_add_f32_e32 v34, v98, v34
	v_exp_f32_e32 v70, v70
	v_sub_f32_e32 v75, v166, v10
	v_add_f32_e32 v34, v103, v34
	v_exp_f32_e32 v75, v75
	v_sub_f32_e32 v79, v167, v10
	v_add_f32_e32 v34, v104, v34
	v_exp_f32_e32 v80, v79
	v_sub_f32_e32 v79, v168, v10
	v_add_f32_e32 v34, v63, v34
	v_exp_f32_e32 v101, v79
	v_sub_f32_e32 v77, v77, v10
	v_add_f32_e32 v34, v70, v34
	v_exp_f32_e32 v155, v77
	v_sub_f32_e32 v76, v76, v10
	v_add_f32_e32 v34, v75, v34
	v_exp_f32_e32 v159, v76
	v_sub_f32_e32 v74, v74, v10
	v_add_f32_e32 v34, v80, v34
	v_exp_f32_e32 v163, v74
	v_sub_f32_e32 v73, v73, v10
	v_add_f32_e32 v34, v101, v34
	v_exp_f32_e32 v74, v73
	v_sub_f32_e32 v66, v66, v10
	v_add_f32_e32 v34, v155, v34
	v_exp_f32_e32 v102, v66
	v_sub_f32_e32 v64, v64, v10
	v_add_f32_e32 v34, v159, v34
	v_exp_f32_e32 v153, v64
	v_sub_f32_e32 v61, v61, v10
	v_add_f32_e32 v34, v163, v34
	v_exp_f32_e32 v154, v61
	v_sub_f32_e32 v58, v58, v10
	v_add_f32_e32 v34, v74, v34
	v_exp_f32_e32 v157, v58
	v_sub_f32_e32 v57, v57, v10
	v_add_f32_e32 v34, v102, v34
	v_exp_f32_e32 v166, v57
	v_sub_f32_e32 v55, v55, v10
	v_add_f32_e32 v34, v153, v34
	v_exp_f32_e32 v167, v55
	v_sub_f32_e32 v53, v53, v10
	v_add_f32_e32 v34, v154, v34
	v_exp_f32_e32 v168, v53
	v_sub_f32_e32 v52, v52, v10
	v_add_f32_e32 v34, v157, v34
	v_exp_f32_e32 v109, v52
	v_sub_f32_e32 v33, v33, v10
	v_add_f32_e32 v34, v166, v34
	v_exp_f32_e32 v156, v33
	v_sub_f32_e32 v32, v32, v10
	v_add_f32_e32 v34, v167, v34
	v_exp_f32_e32 v158, v32
	v_sub_f32_e32 v31, v31, v10
	v_add_f32_e32 v34, v168, v34
	v_exp_f32_e32 v160, v31
	v_sub_f32_e32 v30, v30, v10
	v_add_f32_e32 v34, v109, v34
	v_exp_f32_e32 v161, v30
	v_sub_f32_e32 v29, v29, v10
	v_add_f32_e32 v33, v156, v34
	v_exp_f32_e32 v162, v29
	v_sub_f32_e32 v28, v28, v10
	v_add_f32_e32 v32, v158, v33
	v_exp_f32_e32 v164, v28
	v_sub_f32_e32 v27, v27, v10
	v_add_f32_e32 v31, v160, v32
	v_exp_f32_e32 v165, v27
	v_sub_f32_e32 v26, v26, v10
	v_add_f32_e32 v30, v161, v31
	v_exp_f32_e32 v73, v26
	v_sub_f32_e32 v25, v25, v10
	v_add_f32_e32 v29, v162, v30
	v_exp_f32_e32 v76, v25
	v_sub_f32_e32 v24, v24, v10
	v_add_f32_e32 v28, v164, v29
	v_exp_f32_e32 v77, v24
	v_sub_f32_e32 v23, v23, v10
	v_add_f32_e32 v27, v165, v28
	v_exp_f32_e32 v79, v23
	v_sub_f32_e32 v22, v22, v10
	v_add_f32_e32 v26, v73, v27
	v_exp_f32_e32 v81, v22
	v_sub_f32_e32 v21, v21, v10
	v_add_f32_e32 v25, v76, v26
	v_exp_f32_e32 v99, v21
	v_sub_f32_e32 v20, v20, v10
	v_add_f32_e32 v24, v77, v25
	v_exp_f32_e32 v100, v20
	v_sub_f32_e32 v19, v19, v10
	v_add_u32_e32 v105, v130, v131
	v_add_f32_e32 v23, v79, v24
	v_exp_f32_e32 v108, v19
	v_sub_f32_e32 v18, v18, v10
	v_cvt_pk_bf16_f32 v2, v2, v3
	v_cvt_pk_bf16_f32 v3, v4, v5
	v_cvt_pk_bf16_f32 v4, v6, v7
	v_cvt_pk_bf16_f32 v5, v8, v9
	ds_read_b128 v[6:9], v105 offset:36864
	v_add_f32_e32 v22, v81, v23
	v_exp_f32_e32 v52, v18
	v_sub_f32_e32 v17, v17, v10
	v_add_f32_e32 v21, v99, v22
	v_exp_f32_e32 v53, v17
	v_sub_f32_e32 v16, v16, v10
	v_add_f32_e32 v20, v100, v21
	v_exp_f32_e32 v55, v16
	v_sub_f32_e32 v15, v15, v10
	v_add_f32_e32 v19, v108, v20
	v_exp_f32_e32 v57, v15
	v_sub_f32_e32 v14, v14, v10
	v_add_f32_e32 v18, v52, v19
	v_exp_f32_e32 v58, v14
	v_sub_f32_e32 v13, v13, v10
	v_add_f32_e32 v17, v53, v18
	v_exp_f32_e32 v61, v13
	v_sub_f32_e32 v12, v12, v10
	v_add_f32_e32 v16, v55, v17
	v_exp_f32_e32 v64, v12
	v_sub_f32_e32 v11, v11, v10
	v_add_f32_e32 v15, v57, v16
	v_exp_f32_e32 v66, v11
	v_add_u32_e32 v106, v130, v132
	v_add_f32_e32 v14, v58, v15
	s_waitcnt lgkmcnt(0)
	v_mfma_f32_32x32x16_bf16 v[18:33], v[6:9], v[2:5], 0
	ds_read_b128 v[6:9], v106 offset:36864
	v_cvt_pk_bf16_f32 v170, v35, v36
	v_cvt_pk_bf16_f32 v171, v38, v39
	v_cvt_pk_bf16_f32 v172, v40, v45
	v_cvt_pk_bf16_f32 v173, v48, v51
	ds_read_b128 v[174:177], v105 offset:36896
	v_add_f32_e32 v13, v61, v14
	v_add_f32_e32 v12, v64, v13
	v_add_f32_e32 v11, v66, v12
	ds_bpermute_b32 v12, v129, v11
	v_fma_f32 v10, v149, s94, -v10
	v_exp_f32_e32 v10, v10
	s_waitcnt lgkmcnt(1)
	v_mfma_f32_32x32x16_bf16 v[18:33], v[174:177], v[170:173], v[18:33]
	s_waitcnt lgkmcnt(0)
	v_add_f32_e32 v11, v11, v12
	ds_read_b128 v[174:177], v106 offset:36896
	v_add_f32_e32 v34, v10, v11
	v_add_u32_e32 v107, v133, v131
	v_cvt_pk_bf16_f32 v36, v37, v41
	v_cvt_pk_bf16_f32 v37, v43, v44
	v_cvt_pk_bf16_f32 v38, v47, v56
	v_mfma_f32_32x32x16_bf16 v[2:17], v[6:9], v[2:5], 0
	v_cvt_pk_bf16_f32 v39, v62, v67
	v_add_u32_e32 v106, v133, v132
	v_add_u32_e32 v105, v134, v131
	v_div_scale_f32 v35, vcc, v34, v34, 1.0
	s_waitcnt lgkmcnt(0)
	v_mfma_f32_32x32x16_bf16 v[2:17], v[174:177], v[170:173], v[2:17]
	ds_read_b128 v[178:181], v107 offset:36864
	ds_read_b128 v[182:185], v106 offset:36864
	ds_read_b128 v[186:189], v107 offset:36896
	s_waitcnt lgkmcnt(2)
	v_mfma_f32_32x32x16_bf16 v[18:33], v[178:181], v[36:39], v[18:33]
	ds_read_b128 v[190:193], v106 offset:36896
	s_waitcnt lgkmcnt(2)
	v_mfma_f32_32x32x16_bf16 v[2:17], v[182:185], v[36:39], v[2:17]
	v_cvt_pk_bf16_f32 v36, v42, v46
	v_cvt_pk_bf16_f32 v37, v50, v54
	v_cvt_pk_bf16_f32 v38, v59, v69
	v_cvt_pk_bf16_f32 v39, v72, v78
	ds_read_b128 v[178:181], v105 offset:36864
	s_waitcnt lgkmcnt(2)
	v_mfma_f32_32x32x16_bf16 v[18:33], v[186:189], v[36:39], v[18:33]
	v_add_u32_e32 v194, v134, v132
	ds_read_b128 v[182:185], v194 offset:36864
	s_waitcnt lgkmcnt(2)
	v_mfma_f32_32x32x16_bf16 v[2:17], v[190:193], v[36:39], v[2:17]
	v_cvt_pk_bf16_f32 v36, v49, v60
	v_cvt_pk_bf16_f32 v37, v65, v68
	v_cvt_pk_bf16_f32 v38, v71, v98
	v_cvt_pk_bf16_f32 v39, v103, v104
	v_add_u32_e32 v104, v134, v132
	v_add_u32_e32 v103, v135, v131
	ds_read_b128 v[186:189], v105 offset:36896
	s_waitcnt lgkmcnt(2)
	v_mfma_f32_32x32x16_bf16 v[18:33], v[178:181], v[36:39], v[18:33]
	v_or_b32_e32 v98, s88, v152
	ds_read_b128 v[190:193], v104 offset:36896
	s_waitcnt lgkmcnt(2)
	v_mfma_f32_32x32x16_bf16 v[2:17], v[182:185], v[36:39], v[2:17]
	v_cvt_pk_bf16_f32 v36, v63, v70
	v_cvt_pk_bf16_f32 v37, v75, v80
	v_cvt_pk_bf16_f32 v38, v101, v155
	v_cvt_pk_bf16_f32 v39, v159, v163
	v_add_u32_e32 v101, v136, v131
	ds_read_b128 v[178:181], v103 offset:36864
	s_waitcnt lgkmcnt(2)
	v_mfma_f32_32x32x16_bf16 v[18:33], v[186:189], v[36:39], v[18:33]
	v_add_u32_e32 v202, v135, v132
	ds_read_b128 v[182:185], v202 offset:36864
	s_waitcnt lgkmcnt(2)
	v_mfma_f32_32x32x16_bf16 v[2:17], v[190:193], v[36:39], v[2:17]
	v_cvt_pk_bf16_f32 v36, v74, v102
	v_cvt_pk_bf16_f32 v37, v153, v154
	v_cvt_pk_bf16_f32 v38, v157, v166
	v_cvt_pk_bf16_f32 v39, v167, v168
	v_add_u32_e32 v102, v135, v132
	ds_read_b128 v[186:189], v103 offset:36896
	s_waitcnt lgkmcnt(2)
	v_mfma_f32_32x32x16_bf16 v[18:33], v[178:181], v[36:39], v[18:33]
	ds_read_b128 v[190:193], v102 offset:36896
	s_waitcnt lgkmcnt(2)
	v_mfma_f32_32x32x16_bf16 v[2:17], v[182:185], v[36:39], v[2:17]
	v_cvt_pk_bf16_f32 v36, v109, v156
	v_cvt_pk_bf16_f32 v37, v158, v160
	v_cvt_pk_bf16_f32 v38, v161, v162
	v_cvt_pk_bf16_f32 v39, v164, v165
	ds_read_b128 v[178:181], v101 offset:36864
	s_waitcnt lgkmcnt(2)
	v_mfma_f32_32x32x16_bf16 v[18:33], v[186:189], v[36:39], v[18:33]
	v_add_u32_e32 v203, v136, v132
	ds_read_b128 v[182:185], v203 offset:36864
	s_waitcnt lgkmcnt(2)
	v_mfma_f32_32x32x16_bf16 v[2:17], v[190:193], v[36:39], v[2:17]
	v_cvt_pk_bf16_f32 v36, v73, v76
	v_cvt_pk_bf16_f32 v37, v77, v79
	v_cvt_pk_bf16_f32 v38, v81, v99
	v_cvt_pk_bf16_f32 v39, v100, v108
	v_add_u32_e32 v100, v136, v132
	v_mov_b32_e32 v99, s89
	ds_read_b128 v[186:189], v101 offset:36896
	s_waitcnt lgkmcnt(2)
	v_mfma_f32_32x32x16_bf16 v[18:33], v[178:181], v[36:39], v[18:33]
	ds_read_b128 v[190:193], v100 offset:36896
	s_waitcnt lgkmcnt(2)
	v_mfma_f32_32x32x16_bf16 v[2:17], v[182:185], v[36:39], v[2:17]
	v_cvt_pk_bf16_f32 v36, v52, v53
	v_cvt_pk_bf16_f32 v37, v55, v57
	v_cvt_pk_bf16_f32 v38, v58, v61
	v_cvt_pk_bf16_f32 v39, v64, v66
	s_waitcnt lgkmcnt(1)
	v_mfma_f32_32x32x16_bf16 v[18:33], v[186:189], v[36:39], v[18:33]
	s_waitcnt lgkmcnt(0)
	v_mfma_f32_32x32x16_bf16 v[2:17], v[190:193], v[36:39], v[2:17]
	v_rcp_f32_e32 v36, v35
	s_nop 0
	v_fma_f32 v37, -v35, v36, 1.0
	v_fmac_f32_e32 v36, v37, v36
	v_div_scale_f32 v37, vcc, 1.0, v34, 1.0
	v_mul_f32_e32 v38, v37, v36
	v_fma_f32 v39, -v35, v38, v37
	v_fmac_f32_e32 v38, v39, v36
	v_fma_f32 v35, -v35, v38, v37
	v_div_fmas_f32 v35, v35, v36, v38
	v_div_fixup_f32 v36, v35, v34, 1.0
	v_lshlrev_b64 v[34:35], 11, v[98:99]
	v_bfe_u32 v204, v0, 5, 1
	v_lshl_add_u64 v[34:35], v[126:127], 0, v[34:35]
	v_lshlrev_b32_e32 v204, 3, v204
	v_mov_b32_e32 v205, 0
	v_mul_f32_e32 v18, v18, v36
	v_mul_f32_e32 v19, v19, v36
	v_cvt_pk_bf16_f32 v18, v18, v19
	v_mul_f32_e32 v19, v20, v36
	v_mul_f32_e32 v20, v21, v36
	v_cvt_pk_bf16_f32 v19, v19, v20
	v_mul_f32_e32 v20, v22, v36
	v_mul_f32_e32 v21, v23, v36
	v_cvt_pk_bf16_f32 v20, v20, v21
	v_mul_f32_e32 v21, v24, v36
	v_mul_f32_e32 v22, v25, v36
	v_cvt_pk_bf16_f32 v21, v21, v22
	v_lshl_add_u64 v[34:35], v[34:35], 0, v[204:205]
	v_mul_f32_e32 v26, v26, v36
	v_mul_f32_e32 v27, v27, v36
	v_cvt_pk_bf16_f32 v26, v26, v27
	v_mul_f32_e32 v27, v28, v36
	v_mul_f32_e32 v28, v29, v36
	v_cvt_pk_bf16_f32 v27, v27, v28
	v_mul_f32_e32 v28, v30, v36
	v_mul_f32_e32 v29, v31, v36
	v_cvt_pk_bf16_f32 v28, v28, v29
	v_mul_f32_e32 v29, v32, v36
	v_mul_f32_e32 v30, v33, v36
	v_cvt_pk_bf16_f32 v29, v29, v30
	v_permlane32_swap_b32 v18, v20
	v_permlane32_swap_b32 v19, v21
	global_store_dwordx4 v[34:35], v[18:21], off
	v_permlane32_swap_b32 v26, v28
	v_permlane32_swap_b32 v27, v29
	global_store_dwordx4 v[34:35], v[26:29], off offset:32
	v_mul_f32_e32 v2, v2, v36
	v_mul_f32_e32 v3, v3, v36
	v_cvt_pk_bf16_f32 v2, v2, v3
	v_mul_f32_e32 v3, v4, v36
	v_mul_f32_e32 v4, v5, v36
	v_cvt_pk_bf16_f32 v3, v3, v4
	v_mul_f32_e32 v4, v6, v36
	v_mul_f32_e32 v5, v7, v36
	v_cvt_pk_bf16_f32 v4, v4, v5
	v_mul_f32_e32 v5, v8, v36
	v_mul_f32_e32 v6, v9, v36
	v_cvt_pk_bf16_f32 v5, v5, v6
	v_mul_f32_e32 v10, v10, v36
	v_mul_f32_e32 v11, v11, v36
	v_cvt_pk_bf16_f32 v10, v10, v11
	v_mul_f32_e32 v11, v12, v36
	v_mul_f32_e32 v12, v13, v36
	v_cvt_pk_bf16_f32 v11, v11, v12
	v_mul_f32_e32 v12, v14, v36
	v_mul_f32_e32 v13, v15, v36
	v_cvt_pk_bf16_f32 v12, v12, v13
	v_mul_f32_e32 v13, v16, v36
	v_mul_f32_e32 v14, v17, v36
	v_cvt_pk_bf16_f32 v13, v13, v14
	v_permlane32_swap_b32 v2, v4
	v_permlane32_swap_b32 v3, v5
	global_store_dwordx4 v[34:35], v[2:5], off offset:64
	v_permlane32_swap_b32 v10, v12
	v_permlane32_swap_b32 v11, v13
	global_store_dwordx4 v[34:35], v[10:13], off offset:96
	ds_read_b128 v[2:5], v143
	ds_read_b128 v[6:9], v143 offset:32
	s_waitcnt lgkmcnt(1)
	v_mfma_f32_32x32x16_bf16 v[66:81], v[2:5], v[94:97], 0
	ds_read_b128 v[2:5], v143 offset:64
	v_or_b32_e32 v98, s87, v150
	v_or_b32_e32 v98, s88, v98
	s_waitcnt lgkmcnt(1)
	v_mfma_f32_32x32x16_bf16 v[66:81], v[6:9], v[90:93], v[66:81]
	s_waitcnt lgkmcnt(0)
	v_mfma_f32_32x32x16_bf16 v[66:81], v[2:5], v[86:89], v[66:81]
	ds_read_b128 v[2:5], v143 offset:96
	s_waitcnt lgkmcnt(0)
	v_mfma_f32_32x32x16_bf16 v[66:81], v[2:5], v[82:85], v[66:81]
	ds_read_b128 v[2:5], v144
	ds_read_b128 v[6:9], v144 offset:32
	s_waitcnt lgkmcnt(1)
	v_mfma_f32_32x32x16_bf16 v[34:49], v[2:5], v[94:97], 0
	ds_read_b128 v[2:5], v144 offset:64
	s_nop 6
	v_cndmask_b32_e64 v66, v245, v66, s[48:49]
	v_cndmask_b32_e64 v68, v245, v68, s[52:53]
	v_cndmask_b32_e64 v69, v245, v69, s[54:55]
	v_cndmask_b32_e64 v70, v245, v70, s[56:57]
	v_cndmask_b32_e64 v71, v245, v71, s[58:59]
	v_cndmask_b32_e64 v72, v245, v72, s[60:61]
	s_waitcnt lgkmcnt(1)
	v_mfma_f32_32x32x16_bf16 v[34:49], v[6:9], v[90:93], v[34:49]
	v_cndmask_b32_e64 v73, v245, v73, s[62:63]
	v_cndmask_b32_e64 v74, v245, v74, s[64:65]
	v_cndmask_b32_e64 v75, v245, v75, s[66:67]
	v_cndmask_b32_e64 v76, v245, v76, s[68:69]
	v_cndmask_b32_e64 v77, v245, v77, s[70:71]
	v_cndmask_b32_e64 v78, v245, v78, s[72:73]
	v_cndmask_b32_e64 v79, v245, v79, s[74:75]
	s_waitcnt lgkmcnt(0)
	v_mfma_f32_32x32x16_bf16 v[34:49], v[2:5], v[86:89], v[34:49]
	ds_read_b128 v[2:5], v144 offset:96
	v_cndmask_b32_e64 v80, v245, v80, s[76:77]
	v_cndmask_b32_e64 v81, v245, v81, s[78:79]
	s_waitcnt lgkmcnt(0)
	v_mfma_f32_32x32x16_bf16 v[34:49], v[2:5], v[82:85], v[34:49]
	ds_read_b128 v[2:5], v145
	ds_read_b128 v[6:9], v145 offset:32
	s_waitcnt lgkmcnt(1)
	v_mfma_f32_32x32x16_bf16 v[18:33], v[2:5], v[94:97], 0
	ds_read_b128 v[2:5], v145 offset:64
	s_nop 6
	v_cndmask_b32_e64 v42, v42, v245, s[80:81]
	s_waitcnt lgkmcnt(1)
	v_mfma_f32_32x32x16_bf16 v[18:33], v[6:9], v[90:93], v[18:33]
	s_waitcnt lgkmcnt(0)
	v_mfma_f32_32x32x16_bf16 v[18:33], v[2:5], v[86:89], v[18:33]
	ds_read_b128 v[2:5], v145 offset:96
	s_waitcnt lgkmcnt(0)
	v_mfma_f32_32x32x16_bf16 v[18:33], v[2:5], v[82:85], v[18:33]
	ds_read_b128 v[2:5], v146
	ds_read_b128 v[50:53], v146 offset:32
	s_waitcnt lgkmcnt(1)
	v_mfma_f32_32x32x16_bf16 v[2:17], v[2:5], v[94:97], 0
	s_nop 7
	v_cndmask_b32_e64 v108, v18, v245, s[80:81]
	v_cndmask_b32_e64 v109, v19, v245, s[80:81]
	v_cndmask_b32_e64 v150, v20, v245, s[80:81]
	v_cndmask_b32_e64 v156, v26, v245, s[80:81]
	v_cndmask_b32_e64 v157, v27, v245, s[80:81]
	v_cndmask_b32_e64 v158, v28, v245, s[80:81]
	v_cndmask_b32_e64 v159, v29, v245, s[80:81]
	s_waitcnt lgkmcnt(0)
	v_mfma_f32_32x32x16_bf16 v[2:17], v[50:53], v[90:93], v[2:17]
	ds_read_b128 v[50:53], v146 offset:64
	v_cndmask_b32_e64 v160, v30, v245, s[80:81]
	v_cndmask_b32_e64 v161, v31, v245, s[80:81]
	v_cndmask_b32_e64 v162, v32, v245, s[80:81]
	v_cndmask_b32_e64 v163, v33, v245, s[80:81]
	s_waitcnt lgkmcnt(0)
	v_mfma_f32_32x32x16_bf16 v[2:17], v[50:53], v[86:89], v[2:17]
	ds_read_b128 v[50:53], v146 offset:96
	s_waitcnt lgkmcnt(0)
	v_mfma_f32_32x32x16_bf16 v[2:17], v[50:53], v[82:85], v[2:17]
	ds_read_b128 v[50:53], v147
	ds_read_b128 v[152:155], v147 offset:32
	s_waitcnt lgkmcnt(1)
	v_mfma_f32_32x32x16_bf16 v[50:65], v[50:53], v[94:97], 0
	v_cndmask_b32_e64 v94, v46, v245, s[80:81]
	v_cndmask_b32_e64 v95, v47, v245, s[80:81]
	v_cndmask_b32_e64 v96, v48, v245, s[80:81]
	v_cndmask_b32_e64 v97, v49, v245, s[80:81]
	s_waitcnt lgkmcnt(0)
	v_mfma_f32_32x32x16_bf16 v[50:65], v[152:155], v[90:93], v[50:65]
	ds_read_b128 v[90:93], v147 offset:64
	v_cndmask_b32_e64 v152, v22, v245, s[80:81]
	v_cndmask_b32_e64 v153, v23, v245, s[80:81]
	v_cndmask_b32_e64 v154, v24, v245, s[80:81]
	v_cndmask_b32_e64 v155, v25, v245, s[80:81]
	s_waitcnt lgkmcnt(0)
	v_mfma_f32_32x32x16_bf16 v[50:65], v[90:93], v[86:89], v[50:65]
	ds_read_b128 v[86:89], v147 offset:96
	v_cndmask_b32_e64 v90, v41, v245, s[80:81]
	v_cndmask_b32_e64 v91, v43, v245, s[80:81]
	v_cndmask_b32_e64 v92, v44, v245, s[80:81]
	v_cndmask_b32_e64 v93, v45, v245, s[80:81]
	s_waitcnt lgkmcnt(0)
	v_mfma_f32_32x32x16_bf16 v[50:65], v[86:89], v[82:85], v[50:65]
	v_cndmask_b32_e64 v82, v245, v67, s[50:51]
	v_max3_f32 v67, v151, v66, v82
	v_max3_f32 v67, v67, v68, v69
	v_max3_f32 v67, v67, v70, v71
	v_max3_f32 v67, v67, v72, v73
	v_max3_f32 v67, v67, v74, v75
	v_max3_f32 v67, v67, v76, v77
	v_max3_f32 v67, v67, v78, v79
	v_max3_f32 v67, v67, v80, v81
	v_cndmask_b32_e64 v83, v34, v245, s[80:81]
	v_cndmask_b32_e64 v84, v35, v245, s[80:81]
	v_max3_f32 v34, v67, v83, v84
	v_cndmask_b32_e64 v85, v36, v245, s[80:81]
	v_cndmask_b32_e64 v86, v37, v245, s[80:81]
	v_max3_f32 v34, v34, v85, v86
	v_cndmask_b32_e64 v87, v38, v245, s[80:81]
	v_cndmask_b32_e64 v88, v39, v245, s[80:81]
	v_max3_f32 v34, v34, v87, v88
	v_cndmask_b32_e64 v89, v40, v245, s[80:81]
	v_max3_f32 v34, v34, v89, v90
	v_max3_f32 v34, v34, v42, v91
	v_max3_f32 v34, v34, v92, v93
	v_max3_f32 v34, v34, v94, v95
	v_max3_f32 v34, v34, v96, v97
	v_max3_f32 v18, v34, v108, v109
	v_cndmask_b32_e64 v151, v21, v245, s[80:81]
	v_max3_f32 v18, v18, v150, v151
	v_max3_f32 v18, v18, v152, v153
	v_max3_f32 v18, v18, v154, v155
	v_max3_f32 v18, v18, v156, v157
	v_max3_f32 v18, v18, v158, v159
	v_max3_f32 v18, v18, v160, v161
	v_max3_f32 v18, v18, v162, v163
	v_max3_f32 v18, v18, v2, v3
	v_max3_f32 v18, v18, v4, v5
	v_max3_f32 v18, v18, v6, v7
	v_max3_f32 v18, v18, v8, v9
	v_max3_f32 v18, v18, v10, v11
	v_max3_f32 v18, v18, v12, v13
	v_max3_f32 v18, v18, v14, v15
	v_max3_f32 v18, v18, v16, v17
	v_cndmask_b32_e64 v67, v50, v245, s[12:13]
	v_cndmask_b32_e64 v50, v245, v51, s[46:47]
	v_max3_f32 v18, v18, v67, v50
	v_cndmask_b32_e64 v49, v52, v245, s[16:17]
	v_cndmask_b32_e64 v48, v53, v245, s[18:19]
	v_max3_f32 v18, v18, v49, v48
	v_cndmask_b32_e64 v47, v54, v245, s[20:21]
	v_cndmask_b32_e64 v45, v55, v245, s[22:23]
	v_max3_f32 v18, v18, v47, v45
	v_cndmask_b32_e64 v43, v56, v245, s[24:25]
	v_cndmask_b32_e64 v40, v57, v245, s[26:27]
	v_max3_f32 v18, v18, v43, v40
	v_cndmask_b32_e64 v34, v58, v245, s[28:29]
	v_cndmask_b32_e64 v33, v59, v245, s[30:31]
	v_max3_f32 v18, v18, v34, v33
	v_cndmask_b32_e64 v32, v60, v245, s[34:35]
	v_cndmask_b32_e64 v31, v61, v245, s[36:37]
	v_max3_f32 v18, v18, v32, v31
	v_cndmask_b32_e64 v30, v62, v245, s[38:39]
	v_cndmask_b32_e64 v29, v63, v245, s[42:43]
	v_max3_f32 v18, v18, v30, v29
	v_cndmask_b32_e64 v28, v64, v245, s[44:45]
	v_cndmask_b32_e64 v27, v65, v245, s[0:1]
	v_max3_f32 v18, v18, v28, v27
	v_mov_b32_e32 v19, v18
	v_mov_b32_e32 v206, v18
	s_nop 1
	v_permlane32_swap_b32 v19, v206
	v_max_f32_e32 v26, v19, v206
	v_sub_f32_e32 v18, v66, v26
	v_exp_f32_e32 v18, v18
	v_sub_f32_e32 v19, v82, v26
	v_exp_f32_e32 v19, v19
	v_sub_f32_e32 v38, v76, v26
	v_add_f32_e32 v20, 0, v18
	v_exp_f32_e32 v38, v38
	v_add_f32_e32 v21, v19, v20
	v_sub_f32_e32 v20, v68, v26
	v_exp_f32_e32 v20, v20
	v_sub_f32_e32 v39, v77, v26
	v_exp_f32_e32 v39, v39
	v_sub_f32_e32 v41, v78, v26
	v_add_f32_e32 v22, v20, v21
	v_sub_f32_e32 v21, v69, v26
	v_exp_f32_e32 v21, v21
	v_exp_f32_e32 v44, v41
	v_sub_f32_e32 v41, v79, v26
	v_exp_f32_e32 v54, v41
	v_add_f32_e32 v23, v21, v22
	v_sub_f32_e32 v22, v70, v26
	v_exp_f32_e32 v22, v22
	v_sub_f32_e32 v41, v80, v26
	v_exp_f32_e32 v58, v41
	v_sub_f32_e32 v41, v81, v26
	v_add_f32_e32 v24, v22, v23
	v_sub_f32_e32 v23, v71, v26
	v_exp_f32_e32 v23, v23
	v_exp_f32_e32 v60, v41
	v_sub_f32_e32 v53, v87, v26
	v_exp_f32_e32 v56, v53
	v_add_f32_e32 v25, v23, v24
	v_sub_f32_e32 v24, v72, v26
	v_exp_f32_e32 v24, v24
	v_sub_f32_e32 v53, v88, v26
	v_exp_f32_e32 v63, v53
	v_sub_f32_e32 v53, v89, v26
	v_add_f32_e32 v35, v24, v25
	v_sub_f32_e32 v25, v73, v26
	v_exp_f32_e32 v25, v25
	v_exp_f32_e32 v70, v53
	v_sub_f32_e32 v53, v90, v26
	v_sub_f32_e32 v42, v42, v26
	v_add_f32_e32 v36, v25, v35
	v_sub_f32_e32 v35, v74, v26
	v_exp_f32_e32 v35, v35
	v_exp_f32_e32 v42, v42
	v_sub_f32_e32 v55, v92, v26
	v_exp_f32_e32 v57, v55
	v_add_f32_e32 v37, v35, v36
	v_sub_f32_e32 v36, v75, v26
	v_exp_f32_e32 v36, v36
	v_exp_f32_e32 v75, v53
	v_sub_f32_e32 v53, v91, v26
	v_exp_f32_e32 v53, v53
	v_add_f32_e32 v37, v36, v37
	v_add_f32_e32 v37, v38, v37
	v_add_f32_e32 v37, v39, v37
	v_add_f32_e32 v37, v44, v37
	v_add_f32_e32 v37, v54, v37
	v_add_f32_e32 v37, v58, v37
	v_add_f32_e32 v41, v60, v37
	v_sub_f32_e32 v37, v83, v26
	v_exp_f32_e32 v37, v37
	v_sub_f32_e32 v55, v93, v26
	v_exp_f32_e32 v59, v55
	v_sub_f32_e32 v55, v94, v26
	v_add_f32_e32 v46, v37, v41
	v_sub_f32_e32 v41, v84, v26
	v_exp_f32_e32 v41, v41
	v_exp_f32_e32 v66, v55
	v_sub_f32_e32 v55, v95, v26
	v_exp_f32_e32 v78, v55
	v_add_f32_e32 v51, v41, v46
	v_sub_f32_e32 v46, v85, v26
	v_exp_f32_e32 v46, v46
	v_sub_f32_e32 v55, v96, v26
	v_exp_f32_e32 v82, v55
	v_sub_f32_e32 v55, v97, v26
	v_add_f32_e32 v52, v46, v51
	v_sub_f32_e32 v51, v86, v26
	v_exp_f32_e32 v51, v51
	v_exp_f32_e32 v85, v55
	v_sub_f32_e32 v55, v108, v26
	v_exp_f32_e32 v55, v55
	v_add_f32_e32 v52, v51, v52
	v_add_f32_e32 v52, v56, v52
	v_add_f32_e32 v52, v63, v52
	v_add_f32_e32 v52, v70, v52
	v_add_f32_e32 v52, v75, v52
	v_add_f32_e32 v52, v42, v52
	v_add_f32_e32 v52, v53, v52
	v_add_f32_e32 v52, v57, v52
	v_add_f32_e32 v52, v59, v52
	v_add_f32_e32 v52, v66, v52
	v_sub_f32_e32 v61, v109, v26
	v_add_f32_e32 v52, v78, v52
	v_exp_f32_e32 v62, v61
	v_sub_f32_e32 v61, v150, v26
	v_add_f32_e32 v52, v82, v52
	v_exp_f32_e32 v68, v61
	v_sub_f32_e32 v61, v151, v26
	v_add_f32_e32 v52, v85, v52
	v_exp_f32_e32 v74, v61
	v_sub_f32_e32 v61, v152, v26
	v_add_f32_e32 v52, v55, v52
	v_exp_f32_e32 v80, v61
	v_sub_f32_e32 v61, v153, v26
	v_add_f32_e32 v52, v62, v52
	v_exp_f32_e32 v88, v61
	v_sub_f32_e32 v61, v154, v26
	v_add_f32_e32 v52, v68, v52
	v_exp_f32_e32 v94, v61
	v_sub_f32_e32 v61, v155, v26
	v_add_f32_e32 v52, v74, v52
	v_exp_f32_e32 v109, v61
	v_sub_f32_e32 v61, v156, v26
	v_add_f32_e32 v52, v80, v52
	v_exp_f32_e32 v64, v61
	v_sub_f32_e32 v61, v157, v26
	v_add_f32_e32 v52, v88, v52
	v_exp_f32_e32 v77, v61
	v_sub_f32_e32 v61, v158, v26
	v_add_f32_e32 v52, v94, v52
	v_exp_f32_e32 v81, v61
	v_sub_f32_e32 v61, v159, v26
	v_add_f32_e32 v52, v109, v52
	v_exp_f32_e32 v83, v61
	v_sub_f32_e32 v61, v160, v26
	v_add_f32_e32 v52, v64, v52
	v_exp_f32_e32 v90, v61
	v_sub_f32_e32 v61, v161, v26
	v_add_f32_e32 v52, v77, v52
	v_exp_f32_e32 v150, v61
	v_sub_f32_e32 v61, v162, v26
	v_add_f32_e32 v52, v81, v52
	v_exp_f32_e32 v152, v61
	v_sub_f32_e32 v61, v163, v26
	v_add_f32_e32 v52, v83, v52
	v_exp_f32_e32 v153, v61
	v_sub_f32_e32 v2, v2, v26
	v_add_f32_e32 v52, v90, v52
	v_exp_f32_e32 v79, v2
	v_sub_f32_e32 v3, v3, v26
	v_add_f32_e32 v52, v150, v52
	v_exp_f32_e32 v86, v3
	v_sub_f32_e32 v3, v4, v26
	v_add_f32_e32 v52, v152, v52
	v_exp_f32_e32 v92, v3
	v_sub_f32_e32 v3, v5, v26
	v_add_f32_e32 v52, v153, v52
	v_exp_f32_e32 v97, v3
	v_sub_f32_e32 v3, v6, v26
	v_add_f32_e32 v2, v79, v52
	v_exp_f32_e32 v151, v3
	v_sub_f32_e32 v3, v7, v26
	v_add_f32_e32 v2, v86, v2
	v_exp_f32_e32 v154, v3
	v_sub_f32_e32 v3, v8, v26
	v_add_f32_e32 v2, v92, v2
	v_exp_f32_e32 v155, v3
	v_sub_f32_e32 v3, v9, v26
	v_add_f32_e32 v2, v97, v2
	v_exp_f32_e32 v156, v3
	v_sub_f32_e32 v3, v10, v26
	v_add_f32_e32 v2, v151, v2
	v_exp_f32_e32 v84, v3
	v_sub_f32_e32 v3, v11, v26
	v_add_f32_e32 v2, v154, v2
	v_exp_f32_e32 v87, v3
	v_sub_f32_e32 v3, v12, v26
	v_add_f32_e32 v2, v155, v2
	v_exp_f32_e32 v89, v3
	v_sub_f32_e32 v3, v13, v26
	v_add_f32_e32 v2, v156, v2
	v_exp_f32_e32 v91, v3
	v_sub_f32_e32 v3, v14, v26
	v_add_f32_e32 v2, v84, v2
	v_exp_f32_e32 v93, v3
	v_sub_f32_e32 v3, v15, v26
	v_add_f32_e32 v2, v87, v2
	v_exp_f32_e32 v95, v3
	v_sub_f32_e32 v3, v16, v26
	v_add_f32_e32 v2, v89, v2
	v_exp_f32_e32 v96, v3
	v_sub_f32_e32 v3, v17, v26
	v_add_f32_e32 v2, v91, v2
	v_exp_f32_e32 v108, v3
	v_sub_f32_e32 v3, v67, v26
	v_add_f32_e32 v2, v93, v2
	v_exp_f32_e32 v61, v3
	v_sub_f32_e32 v3, v50, v26
	v_add_f32_e32 v2, v95, v2
	v_exp_f32_e32 v65, v3
	v_sub_f32_e32 v3, v49, v26
	v_add_f32_e32 v2, v96, v2
	v_exp_f32_e32 v67, v3
	v_sub_f32_e32 v3, v48, v26
	v_add_f32_e32 v2, v108, v2
	v_exp_f32_e32 v69, v3
	v_sub_f32_e32 v3, v47, v26
	v_add_f32_e32 v2, v61, v2
	v_exp_f32_e32 v71, v3
	v_sub_f32_e32 v3, v45, v26
	v_add_f32_e32 v2, v65, v2
	v_exp_f32_e32 v72, v3
	v_sub_f32_e32 v3, v43, v26
	v_add_f32_e32 v2, v67, v2
	v_exp_f32_e32 v73, v3
	v_sub_f32_e32 v3, v40, v26
	v_add_f32_e32 v2, v69, v2
	v_exp_f32_e32 v76, v3
	v_sub_f32_e32 v3, v34, v26
	v_add_f32_e32 v2, v71, v2
	v_exp_f32_e32 v40, v3
	v_sub_f32_e32 v3, v33, v26
	v_add_f32_e32 v2, v72, v2
	v_exp_f32_e32 v43, v3
	v_sub_f32_e32 v3, v32, v26
	v_add_f32_e32 v2, v73, v2
	v_exp_f32_e32 v45, v3
	v_sub_f32_e32 v3, v31, v26
	v_add_f32_e32 v2, v76, v2
	v_exp_f32_e32 v47, v3
	v_sub_f32_e32 v3, v30, v26
	v_add_f32_e32 v2, v40, v2
	v_exp_f32_e32 v48, v3
	v_sub_f32_e32 v3, v29, v26
	v_add_f32_e32 v2, v43, v2
	v_exp_f32_e32 v49, v3
	v_sub_f32_e32 v3, v28, v26
	v_add_f32_e32 v2, v45, v2
	v_exp_f32_e32 v50, v3
	v_sub_f32_e32 v3, v27, v26
	v_add_f32_e32 v2, v47, v2
	v_exp_f32_e32 v52, v3
	v_add_f32_e32 v2, v48, v2
	v_add_f32_e32 v2, v49, v2
	v_add_f32_e32 v2, v50, v2
	v_add_f32_e32 v2, v52, v2
	v_mov_b32_e32 v3, v2
	v_mov_b32_e32 v206, v2
	s_nop 1
	v_permlane32_swap_b32 v3, v206
	v_add_f32_e32 v2, v3, v206
	v_fma_f32 v3, v149, s94, -v26
	v_exp_f32_e32 v3, v3
	s_nop 0
	v_add_f32_e32 v34, v3, v2
	v_cvt_pk_bf16_f32 v2, v18, v19
	v_cvt_pk_bf16_f32 v3, v20, v21
	v_cvt_pk_bf16_f32 v4, v22, v23
	v_cvt_pk_bf16_f32 v5, v24, v25
	ds_read_b128 v[6:9], v107 offset:36864
	s_waitcnt lgkmcnt(0)
	v_mfma_f32_32x32x16_bf16 v[18:33], v[6:9], v[2:5], 0
	ds_read_b128 v[6:9], v106 offset:36864
	v_cvt_pk_bf16_f32 v158, v35, v36
	v_cvt_pk_bf16_f32 v159, v38, v39
	v_cvt_pk_bf16_f32 v160, v44, v54
	v_cvt_pk_bf16_f32 v161, v58, v60
	ds_read_b128 v[162:165], v107 offset:36896
	v_add_u32_e32 v35, v137, v131
	s_waitcnt lgkmcnt(0)
	v_mfma_f32_32x32x16_bf16 v[18:33], v[162:165], v[158:161], v[18:33]
	ds_read_b128 v[162:165], v106 offset:36896
	v_cvt_pk_bf16_f32 v36, v37, v41
	v_cvt_pk_bf16_f32 v37, v46, v51
	v_cvt_pk_bf16_f32 v38, v56, v63
	v_cvt_pk_bf16_f32 v39, v70, v75
	v_add_u32_e32 v44, v137, v132
	v_mfma_f32_32x32x16_bf16 v[2:17], v[6:9], v[2:5], 0
	s_waitcnt lgkmcnt(0)
	v_mfma_f32_32x32x16_bf16 v[2:17], v[162:165], v[158:161], v[2:17]
	ds_read_b128 v[178:181], v105 offset:36864
	ds_read_b128 v[182:185], v104 offset:36864
	ds_read_b128 v[186:189], v105 offset:36896
	s_waitcnt lgkmcnt(2)
	v_mfma_f32_32x32x16_bf16 v[18:33], v[178:181], v[36:39], v[18:33]
	ds_read_b128 v[190:193], v104 offset:36896
	s_waitcnt lgkmcnt(2)
	v_mfma_f32_32x32x16_bf16 v[2:17], v[182:185], v[36:39], v[2:17]
	v_cvt_pk_bf16_f32 v36, v42, v53
	v_cvt_pk_bf16_f32 v37, v57, v59
	v_cvt_pk_bf16_f32 v38, v66, v78
	v_cvt_pk_bf16_f32 v39, v82, v85
	ds_read_b128 v[178:181], v103 offset:36864
	s_waitcnt lgkmcnt(2)
	v_mfma_f32_32x32x16_bf16 v[18:33], v[186:189], v[36:39], v[18:33]
	ds_read_b128 v[182:185], v102 offset:36864
	s_waitcnt lgkmcnt(2)
	v_mfma_f32_32x32x16_bf16 v[2:17], v[190:193], v[36:39], v[2:17]
	v_cvt_pk_bf16_f32 v36, v55, v62
	v_cvt_pk_bf16_f32 v37, v68, v74
	v_cvt_pk_bf16_f32 v38, v80, v88
	v_cvt_pk_bf16_f32 v39, v94, v109
	ds_read_b128 v[186:189], v103 offset:36896
	s_waitcnt lgkmcnt(2)
	v_mfma_f32_32x32x16_bf16 v[18:33], v[178:181], v[36:39], v[18:33]
	ds_read_b128 v[190:193], v102 offset:36896
	s_waitcnt lgkmcnt(2)
	v_mfma_f32_32x32x16_bf16 v[2:17], v[182:185], v[36:39], v[2:17]
	v_cvt_pk_bf16_f32 v36, v64, v77
	v_cvt_pk_bf16_f32 v37, v81, v83
	v_cvt_pk_bf16_f32 v38, v90, v150
	v_cvt_pk_bf16_f32 v39, v152, v153
	ds_read_b128 v[178:181], v101 offset:36864
	s_waitcnt lgkmcnt(2)
	v_mfma_f32_32x32x16_bf16 v[18:33], v[186:189], v[36:39], v[18:33]
	ds_read_b128 v[182:185], v100 offset:36864
	s_waitcnt lgkmcnt(2)
	v_mfma_f32_32x32x16_bf16 v[2:17], v[190:193], v[36:39], v[2:17]
	v_cvt_pk_bf16_f32 v36, v79, v86
	v_cvt_pk_bf16_f32 v37, v92, v97
	v_cvt_pk_bf16_f32 v38, v151, v154
	v_cvt_pk_bf16_f32 v39, v155, v156
	ds_read_b128 v[186:189], v101 offset:36896
	s_waitcnt lgkmcnt(2)
	v_mfma_f32_32x32x16_bf16 v[18:33], v[178:181], v[36:39], v[18:33]
	ds_read_b128 v[190:193], v100 offset:36896
	s_waitcnt lgkmcnt(2)
	v_mfma_f32_32x32x16_bf16 v[2:17], v[182:185], v[36:39], v[2:17]
	v_cvt_pk_bf16_f32 v36, v84, v87
	v_cvt_pk_bf16_f32 v37, v89, v91
	v_cvt_pk_bf16_f32 v38, v93, v95
	v_cvt_pk_bf16_f32 v39, v96, v108
	ds_read_b128 v[178:181], v35 offset:36864
	s_waitcnt lgkmcnt(2)
	v_mfma_f32_32x32x16_bf16 v[18:33], v[186:189], v[36:39], v[18:33]
	ds_read_b128 v[182:185], v44 offset:36864
	s_waitcnt lgkmcnt(2)
	v_mfma_f32_32x32x16_bf16 v[2:17], v[190:193], v[36:39], v[2:17]
	v_cvt_pk_bf16_f32 v36, v61, v65
	v_cvt_pk_bf16_f32 v37, v67, v69
	v_cvt_pk_bf16_f32 v38, v71, v72
	v_cvt_pk_bf16_f32 v39, v73, v76
	ds_read_b128 v[186:189], v35 offset:36896
	s_waitcnt lgkmcnt(2)
	v_mfma_f32_32x32x16_bf16 v[18:33], v[178:181], v[36:39], v[18:33]
	ds_read_b128 v[190:193], v44 offset:36896
	s_waitcnt lgkmcnt(2)
	v_mfma_f32_32x32x16_bf16 v[2:17], v[182:185], v[36:39], v[2:17]
	v_cvt_pk_bf16_f32 v36, v40, v43
	v_cvt_pk_bf16_f32 v37, v45, v47
	v_cvt_pk_bf16_f32 v38, v48, v49
	v_cvt_pk_bf16_f32 v39, v50, v52
	v_div_scale_f32 v35, s[48:49], v34, v34, 1.0
	s_waitcnt lgkmcnt(1)
	v_mfma_f32_32x32x16_bf16 v[18:33], v[186:189], v[36:39], v[18:33]
	s_waitcnt lgkmcnt(0)
	v_mfma_f32_32x32x16_bf16 v[2:17], v[190:193], v[36:39], v[2:17]
	v_rcp_f32_e32 v36, v35
	s_nop 0
	v_fma_f32 v37, -v35, v36, 1.0
	v_fmac_f32_e32 v36, v37, v36
	v_div_scale_f32 v37, vcc, 1.0, v34, 1.0
	v_mul_f32_e32 v38, v37, v36
	v_fma_f32 v39, -v35, v38, v37
	v_fmac_f32_e32 v38, v39, v36
	v_fma_f32 v35, -v35, v38, v37
	v_div_fmas_f32 v35, v35, v36, v38
	v_div_fixup_f32 v36, v35, v34, 1.0
	v_lshlrev_b64 v[34:35], 11, v[98:99]
	v_bfe_u32 v204, v0, 5, 1
	v_lshl_add_u64 v[34:35], v[126:127], 0, v[34:35]
	v_lshlrev_b32_e32 v204, 3, v204
	v_mov_b32_e32 v205, 0
	v_mul_f32_e32 v18, v18, v36
	v_mul_f32_e32 v19, v19, v36
	v_cvt_pk_bf16_f32 v18, v18, v19
	v_mul_f32_e32 v19, v20, v36
	v_mul_f32_e32 v20, v21, v36
	v_cvt_pk_bf16_f32 v19, v19, v20
	v_mul_f32_e32 v20, v22, v36
	v_mul_f32_e32 v21, v23, v36
	v_cvt_pk_bf16_f32 v20, v20, v21
	v_mul_f32_e32 v21, v24, v36
	v_mul_f32_e32 v22, v25, v36
	v_cvt_pk_bf16_f32 v21, v21, v22
	v_lshl_add_u64 v[34:35], v[34:35], 0, v[204:205]
	v_mul_f32_e32 v26, v26, v36
	v_mul_f32_e32 v27, v27, v36
	v_cvt_pk_bf16_f32 v26, v26, v27
	v_mul_f32_e32 v27, v28, v36
	v_mul_f32_e32 v28, v29, v36
	v_cvt_pk_bf16_f32 v27, v27, v28
	v_mul_f32_e32 v28, v30, v36
	v_mul_f32_e32 v29, v31, v36
	v_cvt_pk_bf16_f32 v28, v28, v29
	v_mul_f32_e32 v29, v32, v36
	v_mul_f32_e32 v30, v33, v36
	v_cvt_pk_bf16_f32 v29, v29, v30
	v_permlane32_swap_b32 v18, v20
	v_permlane32_swap_b32 v19, v21
	global_store_dwordx4 v[34:35], v[18:21], off
	v_permlane32_swap_b32 v26, v28
	v_permlane32_swap_b32 v27, v29
	global_store_dwordx4 v[34:35], v[26:29], off offset:32
	v_mul_f32_e32 v2, v2, v36
	v_mul_f32_e32 v3, v3, v36
	v_cvt_pk_bf16_f32 v2, v2, v3
	v_mul_f32_e32 v3, v4, v36
	v_mul_f32_e32 v4, v5, v36
	v_cvt_pk_bf16_f32 v3, v3, v4
	v_mul_f32_e32 v4, v6, v36
	v_mul_f32_e32 v5, v7, v36
	v_cvt_pk_bf16_f32 v4, v4, v5
	v_mul_f32_e32 v5, v8, v36
	v_mul_f32_e32 v6, v9, v36
	v_cvt_pk_bf16_f32 v5, v5, v6
	v_mul_f32_e32 v10, v10, v36
	v_mul_f32_e32 v11, v11, v36
	v_cvt_pk_bf16_f32 v10, v10, v11
	v_mul_f32_e32 v11, v12, v36
	v_mul_f32_e32 v12, v13, v36
	v_cvt_pk_bf16_f32 v11, v11, v12
	v_mul_f32_e32 v12, v14, v36
	v_mul_f32_e32 v13, v15, v36
	v_cvt_pk_bf16_f32 v12, v12, v13
	v_mul_f32_e32 v13, v16, v36
	v_mul_f32_e32 v14, v17, v36
	v_cvt_pk_bf16_f32 v13, v13, v14
	v_permlane32_swap_b32 v2, v4
	v_permlane32_swap_b32 v3, v5
	global_store_dwordx4 v[34:35], v[2:5], off offset:64
	v_permlane32_swap_b32 v10, v12
	v_permlane32_swap_b32 v11, v13
	global_store_dwordx4 v[34:35], v[10:13], off offset:96
	s_cbranch_scc0 .LBB0_821
.LBB0_813:
	s_ashr_i32 s50, s2, 7
	s_and_b32 s49, s2, 3
	s_bfe_u32 s80, s2, 0x50002
	s_ashr_i32 s51, s50, 31
	s_lshl_b32 s48, s49, 2
	s_lshl_b64 s[88:89], s[50:51], 12
	v_lshl_or_b32 v150, s80, 7, v128
	s_add_i32 s48, s48, s83
	v_or_b32_e32 v8, s88, v150
	v_mov_b32_e32 v3, s89
	s_lshl_b32 s50, s48, 6
	v_or_b32_e32 v2, s97, v8
	s_ashr_i32 s51, s50, 31
	v_lshlrev_b64 v[6:7], 11, v[2:3]
	v_or_b32_e32 v2, s87, v8
	v_lshl_add_u64 v[4:5], s[50:51], 1, v[110:111]
	v_lshlrev_b64 v[2:3], 11, v[2:3]
	v_lshl_add_u64 v[6:7], v[4:5], 0, v[6:7]
	v_lshl_add_u64 v[2:3], v[4:5], 0, v[2:3]
	global_load_dwordx4 v[34:37], v[6:7], off
	global_load_dwordx4 v[106:109], v[6:7], off offset:32
	global_load_dwordx4 v[102:105], v[6:7], off offset:64
	global_load_dwordx4 v[98:101], v[6:7], off offset:96
	global_load_dwordx4 v[94:97], v[2:3], off
	global_load_dwordx4 v[90:93], v[2:3], off offset:32
	global_load_dwordx4 v[86:89], v[2:3], off offset:64
	global_load_dwordx4 v[82:85], v[2:3], off offset:96
	v_add_co_u32_e64 v2, vcc, s80, -1
	v_ashrrev_i32_e32 v3, 31, v2
	v_lshlrev_b64 v[2:3], 7, v[2:3]
	s_lshl_b32 s94, s49, 7
	v_lshl_add_u64 v[16:17], v[2:3], 0, s[88:89]
	v_lshl_add_u64 v[18:19], v[114:115], 0, s[94:95]
	v_lshl_add_u64 v[20:21], v[116:117], 0, s[94:95]
	v_mov_b32_e32 v38, 0
	v_mov_b32_e32 v39, 0
	v_mov_b32_e32 v40, 0
	v_mov_b32_e32 v41, 0
	v_mov_b32_e32 v42, 0
	v_mov_b32_e32 v43, 0
	v_mov_b32_e32 v44, 0
	v_mov_b32_e32 v45, 0
	v_mov_b32_e32 v46, 0
	v_mov_b32_e32 v47, 0
	v_mov_b32_e32 v48, 0
	v_mov_b32_e32 v49, 0
	v_mov_b32_e32 v50, 0
	v_mov_b32_e32 v51, 0
	v_mov_b32_e32 v52, 0
	v_mov_b32_e32 v53, 0
	v_mov_b32_e32 v54, 0
	v_mov_b32_e32 v55, 0
	v_mov_b32_e32 v56, 0
	v_mov_b32_e32 v57, 0
	v_mov_b32_e32 v58, 0
	v_mov_b32_e32 v59, 0
	v_mov_b32_e32 v60, 0
	v_mov_b32_e32 v61, 0
	v_mov_b32_e32 v62, 0
	v_mov_b32_e32 v63, 0
	v_mov_b32_e32 v64, 0
	v_mov_b32_e32 v65, 0
	v_mov_b32_e32 v66, 0
	v_mov_b32_e32 v67, 0
	v_mov_b32_e32 v68, 0
	v_mov_b32_e32 v69, 0
	s_or_b64 s[54:55], s[4:5], vcc
	s_and_saveexec_b64 s[52:53], s[54:55]
	v_lshl_add_u64 v[70:71], v[16:17], 0, v[112:113]
	v_lshlrev_b64 v[70:71], 9, v[70:71]
	v_lshl_add_u64 v[72:73], v[20:21], 0, v[70:71]
	v_lshl_add_u64 v[70:71], v[18:19], 0, v[70:71]
	global_load_dwordx4 v[38:41], v[70:71], off
	global_load_dwordx4 v[54:57], v[72:73], off
	s_or_b64 exec, exec, s[52:53]
	s_or_b64 s[54:55], s[6:7], vcc
	s_and_saveexec_b64 s[52:53], s[54:55]
	v_lshl_add_u64 v[70:71], v[16:17], 0, v[120:121]
	v_lshlrev_b64 v[70:71], 9, v[70:71]
	v_lshl_add_u64 v[72:73], v[20:21], 0, v[70:71]
	v_lshl_add_u64 v[70:71], v[18:19], 0, v[70:71]
	global_load_dwordx4 v[42:45], v[70:71], off
	global_load_dwordx4 v[58:61], v[72:73], off
	s_or_b64 exec, exec, s[52:53]
	s_or_b64 s[54:55], s[8:9], vcc
	s_and_saveexec_b64 s[52:53], s[54:55]
	v_lshl_add_u64 v[70:71], v[16:17], 0, v[122:123]
	v_lshlrev_b64 v[70:71], 9, v[70:71]
	v_lshl_add_u64 v[72:73], v[20:21], 0, v[70:71]
	v_lshl_add_u64 v[70:71], v[18:19], 0, v[70:71]
	global_load_dwordx4 v[46:49], v[70:71], off
	global_load_dwordx4 v[62:65], v[72:73], off
	s_or_b64 exec, exec, s[52:53]
	s_or_b64 s[54:55], s[10:11], vcc
	s_and_saveexec_b64 s[52:53], s[54:55]
	v_lshl_add_u64 v[70:71], v[16:17], 0, v[124:125]
	v_lshlrev_b64 v[70:71], 9, v[70:71]
	v_lshl_add_u64 v[72:73], v[20:21], 0, v[70:71]
	v_lshl_add_u64 v[70:71], v[18:19], 0, v[70:71]
	global_load_dwordx4 v[50:53], v[70:71], off
	global_load_dwordx4 v[66:69], v[72:73], off
	s_or_b64 exec, exec, s[52:53]
	s_barrier
	v_bfe_u32 v74, v0, 3, 1
	v_mov_b32_e32 v76, 0x5040100
	v_mov_b32_e32 v77, 0x3020706
	v_cmp_ne_u32_e64 s[54:55], 0, v74
	v_mul_u32_u24_e32 v75, 0x20e, v74
	s_nop 0
	v_cndmask_b32_e64 v76, v76, v77, s[54:55]
	v_add_u32_e32 v70, v138, v75
	v_add_u32_e32 v71, v139, v75
	v_add_u32_e32 v72, v140, v75
	v_add_u32_e32 v73, v141, v75
	s_waitcnt vmcnt(7)
	ds_write_b128 v148, v[38:41]
	s_waitcnt vmcnt(6)
	v_mov_b32_dpp v78, v54 row_ror:8 row_mask:0xf bank_mask:0xf
	v_perm_b32 v79, v78, v54, v76
	ds_write_b32 v70, v79 offset:36864
	v_mov_b32_dpp v80, v55 row_ror:8 row_mask:0xf bank_mask:0xf
	v_perm_b32 v81, v80, v55, v76
	ds_write_b32 v70, v81 offset:37920
	v_mov_b32_dpp v78, v56 row_ror:8 row_mask:0xf bank_mask:0xf
	v_perm_b32 v79, v78, v56, v76
	ds_write_b32 v70, v79 offset:38976
	v_mov_b32_dpp v80, v57 row_ror:8 row_mask:0xf bank_mask:0xf
	v_perm_b32 v81, v80, v57, v76
	ds_write_b32 v70, v81 offset:40032
	s_waitcnt vmcnt(5)
	ds_write_b128 v148, v[42:45] offset:9216
	s_waitcnt vmcnt(4)
	v_mov_b32_dpp v78, v58 row_ror:8 row_mask:0xf bank_mask:0xf
	v_perm_b32 v79, v78, v58, v76
	ds_write_b32 v71, v79 offset:36864
	v_mov_b32_dpp v80, v59 row_ror:8 row_mask:0xf bank_mask:0xf
	v_perm_b32 v81, v80, v59, v76
	ds_write_b32 v71, v81 offset:37920
	v_mov_b32_dpp v78, v60 row_ror:8 row_mask:0xf bank_mask:0xf
	v_perm_b32 v79, v78, v60, v76
	ds_write_b32 v71, v79 offset:38976
	v_mov_b32_dpp v80, v61 row_ror:8 row_mask:0xf bank_mask:0xf
	v_perm_b32 v81, v80, v61, v76
	ds_write_b32 v71, v81 offset:40032
	s_waitcnt vmcnt(3)
	ds_write_b128 v148, v[46:49] offset:18432
	s_waitcnt vmcnt(2)
	v_mov_b32_dpp v78, v62 row_ror:8 row_mask:0xf bank_mask:0xf
	v_perm_b32 v79, v78, v62, v76
	ds_write_b32 v72, v79 offset:36864
	v_mov_b32_dpp v80, v63 row_ror:8 row_mask:0xf bank_mask:0xf
	v_perm_b32 v81, v80, v63, v76
	ds_write_b32 v72, v81 offset:37920
	v_mov_b32_dpp v78, v64 row_ror:8 row_mask:0xf bank_mask:0xf
	v_perm_b32 v79, v78, v64, v76
	ds_write_b32 v72, v79 offset:38976
	v_mov_b32_dpp v80, v65 row_ror:8 row_mask:0xf bank_mask:0xf
	v_perm_b32 v81, v80, v65, v76
	ds_write_b32 v72, v81 offset:40032
	s_waitcnt vmcnt(1)
	ds_write_b128 v148, v[50:53] offset:27648
	s_waitcnt vmcnt(0)
	v_mov_b32_dpp v78, v66 row_ror:8 row_mask:0xf bank_mask:0xf
	v_perm_b32 v79, v78, v66, v76
	ds_write_b32 v73, v79 offset:36864
	v_mov_b32_dpp v80, v67 row_ror:8 row_mask:0xf bank_mask:0xf
	v_perm_b32 v81, v80, v67, v76
	ds_write_b32 v73, v81 offset:37920
	v_mov_b32_dpp v78, v68 row_ror:8 row_mask:0xf bank_mask:0xf
	v_perm_b32 v79, v78, v68, v76
	ds_write_b32 v73, v79 offset:38976
	v_mov_b32_dpp v80, v69 row_ror:8 row_mask:0xf bank_mask:0xf
	v_perm_b32 v81, v80, v69, v76
	ds_write_b32 v73, v81 offset:40032
	s_branch .LBB0_812
